# attention phase prologue: the 8 rope-table staging loads per thread issued together (saddr form) with counted waits, instead of 4 serial load-pair round trips
# baseline (speedup 1.0000x reference)
.LBB0_137:
	v_mov_b32_e32 v112, v250
	s_nop 0
	v_readfirstlane_b32 s10, v112
	v_cmp_gt_i32_e32 vcc, s68, v112
	s_and_saveexec_b64 s[0:1], vcc
	s_cbranch_execz .LBB0_150
	s_waitcnt vmcnt(0)
	v_readlane_b32 s12, v252, 24
	v_readlane_b32 s13, v252, 25
	v_lshlrev_b32_e32 v0, 2, v112
	v_add_u32_e32 v1, v179, v0
	s_nop 2
	s_add_u32 s4, s12, 0x1000
	s_addc_u32 s5, s13, 0
	s_add_u32 s6, s12, 0x2000
	s_addc_u32 s7, s13, 0
	s_add_u32 s8, s12, 0x3000
	s_addc_u32 s9, s13, 0
	global_load_dword v2, v0, s[12:13]
	global_load_dword v3, v0, s[12:13] offset:2048
	global_load_dword v4, v0, s[4:5]
	global_load_dword v5, v0, s[4:5] offset:2048
	global_load_dword v6, v0, s[6:7]
	global_load_dword v7, v0, s[6:7] offset:2048
	global_load_dword v8, v0, s[8:9]
	global_load_dword v9, v0, s[8:9] offset:2048
	s_waitcnt vmcnt(6)
	ds_write_b32 v1, v2
	ds_write_b32 v1, v3 offset:2048
	s_waitcnt vmcnt(4)
	ds_write_b32 v1, v4 offset:4096
	ds_write_b32 v1, v5 offset:6144
	s_waitcnt vmcnt(2)
	ds_write_b32 v1, v6 offset:8192
	ds_write_b32 v1, v7 offset:10240
	s_waitcnt vmcnt(0)
	ds_write_b32 v1, v8 offset:12288
	ds_write_b32 v1, v9 offset:14336
